# rwkv scan: identity-row waves start half a step after the value-row waves
# baseline (speedup 1.0000x reference)
; __device__ __forceinline__ int tidx() { int t = threadIdx.x; asm volatile("" : "+v"(t)); return t; }
; __device__ __forceinline__ float bf2f(unsigned short b) { return __uint_as_float((unsigned)b << 16); }
; __device__ __forceinline__ f2 pfma(f2 a, f2 b, f2 c) { return __builtin_elementwise_fma(a, b, c); }
; template <bool ID> __device__ __forceinline__ void rwkv_scan(const bf16_t* __restrict__ R, const bf16_t* __restrict__ EW, const bf16_t* __restrict__ K, const bf16_t* __restrict__ V, ...
;     ...
;     { unsigned o = base; q1[0] = R[o]; q1[1] = EW[o]; q1[2] = K[o]; q1[3] = V[o]; q1[4] = A[o]; q1[5] = B[o];
;       o = base + 512u; q2[0] = R[o]; q2[1] = EW[o]; q2[2] = K[o]; q2[3] = V[o]; q2[4] = A[o]; q2[5] = B[o]; }
;     const LAS f32x4* pa = (const LAS f32x4*)L;
;     float sav, sai;
;     { L[lane] = bf2f(q1[4]);
;       f2 av = {0.f, 0.f}, ai = {0.f, 0.f};
; #pragma unroll
;       for (int q = 0; q < 16; ++q) { const f32x4 a4 = pa[q]; const f2 a01 = {a4[0], a4[1]}, a23 = {a4[2], a4[3]};
;           av = pfma(Sv[2 * q], a01, av); av = pfma(Sv[2 * q + 1], a23, av); if (ID) { ai = pfma(Si[2 * q], a01, ai); ai = pfma(Si[2 * q + 1], a23, ai); } }
;       sav = av[0] + av[1]; sai = ai[0] + ai[1]; }
; #pragma unroll 1
;     for (int s = 0; s < nsteps; ++s) {
;         L[lane] = bf2f(q2[4]); L[64 + lane] = __expf(-bf2f(q1[1])); L[128 + lane] = bf2f(q1[5]); L[192 + lane] = bf2f(q1[2]); L[256 + lane] = bf2f(q1[0]);
; __device__ void phase_rwkv_scan(const Ctx& p, int l, LAS unsigned char* lds) {
;     ...
;             f2 Sv[32], Si[32]; const int li = tidx() & 63;
; #pragma unroll
;             for (int i = 0; i < 32; ++i) { Sv[i] = (f2){0.f, 0.f}; Si[i] = (f2){(2 * i == li) ? 1.f : 0.f, (2 * i + 1 == li) ? 1.f : 0.f}; }
.Lscan_i:
	v_lshrrev_b32_e32 v78, 5, v139
	v_and_b32_e32 v79, 31, v139
	s_mov_b32 s26, -1
	s_mov_b32 s27, 0
	s_lshl_b32 s14, s36, 13
	s_and_b32 s14, s14, 0xffff0000
	s_lshl_b32 s15, s36, 6
	s_and_b32 s15, s15, 0x1c0
	s_or_b32 s14, s14, s15
	v_add_lshl_u32 v72, s14, v139, 1
	v_add_lshl_u32 v81, s14, v79, 1
	v_mov_b32_e32 v74, s20
	v_mov_b32_e32 v75, s21
	v_mov_b32_e32 v80, s6
	v_cndmask_b32_e64 v74, v80, v74, s[26:27]
	v_mov_b32_e32 v80, s7
	v_cndmask_b32_e64 v75, v80, v75, s[26:27]
	v_add_co_u32_e32 v74, vcc, v74, v81
	s_nop 1
	v_addc_co_u32_e32 v75, vcc, 0, v75, vcc
	v_lshl_add_u32 v76, v78, 4, s10
	v_lshl_add_u32 v77, v139, 2, s10
	v_lshlrev_b32_e32 v81, 2, v78
	v_sub_u32_e32 v81, v79, v81
	global_load_ushort v244, v72, s[12:13]
	global_load_ushort v224, v72, s[4:5] offset:0
	global_load_ushort v225, v72, s[0:1] offset:0
	global_load_ushort v226, v72, s[12:13] offset:1024
	global_load_ushort v227, v[74:75], off offset:0
	global_load_ushort v228, v[74:75], off offset:64
	global_load_ushort v230, v72, s[4:5] offset:1024
	global_load_ushort v231, v72, s[0:1] offset:1024
	global_load_ushort v232, v72, s[12:13] offset:2048
	global_load_ushort v233, v[74:75], off offset:1024
	global_load_ushort v234, v[74:75], off offset:1088
	global_load_ushort v82, v72, s[4:5] offset:2048
	global_load_ushort v83, v72, s[0:1] offset:2048
	global_load_ushort v84, v72, s[12:13] offset:3072
	global_load_ushort v85, v[74:75], off offset:2048
	global_load_ushort v86, v[74:75], off offset:2112
	v_add_u32_e32 v72, 0xc00, v72
	v_lshl_add_u64 v[74:75], v[74:75], 0, s[54:55]
	v_lshl_add_u64 v[74:75], v[74:75], 0, s[54:55]
	v_lshl_add_u64 v[74:75], v[74:75], 0, s[54:55]
	global_load_ushort v88, v72, s[4:5] offset:0
	global_load_ushort v89, v72, s[0:1] offset:0
	global_load_ushort v90, v72, s[12:13] offset:1024
	global_load_ushort v91, v[74:75], off offset:0
	global_load_ushort v92, v[74:75], off offset:64
	v_add_u32_e32 v72, 0x400, v72
	v_lshl_add_u64 v[74:75], v[74:75], 0, s[54:55]
	v_mov_b32_e32 v16, 0
	v_mov_b32_e32 v17, 0
	v_mov_b32_e32 v18, 0
	v_mov_b32_e32 v19, 0
	v_mov_b32_e32 v20, 0
	v_mov_b32_e32 v21, 0
	v_mov_b32_e32 v22, 0
	v_mov_b32_e32 v23, 0
	v_mov_b32_e32 v24, 0
	v_mov_b32_e32 v25, 0
	v_mov_b32_e32 v26, 0
	v_mov_b32_e32 v27, 0
	v_mov_b32_e32 v28, 0
	v_mov_b32_e32 v29, 0
	v_mov_b32_e32 v30, 0
	v_mov_b32_e32 v31, 0
	v_mov_b32_e32 v32, 0
	v_mov_b32_e32 v33, 0
	v_mov_b32_e32 v34, 0
	v_mov_b32_e32 v35, 0
	v_mov_b32_e32 v36, 0
	v_mov_b32_e32 v37, 0
	v_mov_b32_e32 v38, 0
	v_mov_b32_e32 v39, 0
	v_mov_b32_e32 v40, 0
	v_mov_b32_e32 v41, 0
	v_mov_b32_e32 v42, 0
	v_mov_b32_e32 v43, 0
	v_mov_b32_e32 v44, 0
	v_mov_b32_e32 v45, 0
	v_mov_b32_e32 v46, 0
	v_mov_b32_e32 v47, 0
	v_cmp_eq_u32_e64 s[14:15], 0, v81
	s_nop 1
	v_cndmask_b32_e64 v0, 0, 1.0, s[14:15]
	v_cndmask_b32_e64 v48, 0, 1.0, s[14:15]
	v_cmp_eq_u32_e64 s[14:15], 1, v81
	s_nop 1
	v_cndmask_b32_e64 v1, 0, 1.0, s[14:15]
	v_cndmask_b32_e64 v49, 0, 1.0, s[14:15]
	v_cmp_eq_u32_e64 s[14:15], 2, v81
	s_nop 1
	v_cndmask_b32_e64 v2, 0, 1.0, s[14:15]
	v_cndmask_b32_e64 v50, 0, 1.0, s[14:15]
	v_cmp_eq_u32_e64 s[14:15], 3, v81
	s_nop 1
	v_cndmask_b32_e64 v3, 0, 1.0, s[14:15]
	v_cndmask_b32_e64 v51, 0, 1.0, s[14:15]
	v_cmp_eq_u32_e64 s[14:15], 8, v81
	s_nop 1
	v_cndmask_b32_e64 v4, 0, 1.0, s[14:15]
	v_cndmask_b32_e64 v52, 0, 1.0, s[14:15]
	v_cmp_eq_u32_e64 s[14:15], 9, v81
	s_nop 1
	v_cndmask_b32_e64 v5, 0, 1.0, s[14:15]
	v_cndmask_b32_e64 v53, 0, 1.0, s[14:15]
	v_cmp_eq_u32_e64 s[14:15], 10, v81
	s_nop 1
	v_cndmask_b32_e64 v6, 0, 1.0, s[14:15]
	v_cndmask_b32_e64 v54, 0, 1.0, s[14:15]
	v_cmp_eq_u32_e64 s[14:15], 11, v81
	s_nop 1
	v_cndmask_b32_e64 v7, 0, 1.0, s[14:15]
	v_cndmask_b32_e64 v55, 0, 1.0, s[14:15]
	v_cmp_eq_u32_e64 s[14:15], 16, v81
	s_nop 1
	v_cndmask_b32_e64 v8, 0, 1.0, s[14:15]
	v_cndmask_b32_e64 v56, 0, 1.0, s[14:15]
	v_cmp_eq_u32_e64 s[14:15], 17, v81
	s_nop 1
	v_cndmask_b32_e64 v9, 0, 1.0, s[14:15]
	v_cndmask_b32_e64 v57, 0, 1.0, s[14:15]
	v_cmp_eq_u32_e64 s[14:15], 18, v81
	s_nop 1
	v_cndmask_b32_e64 v10, 0, 1.0, s[14:15]
	v_cndmask_b32_e64 v58, 0, 1.0, s[14:15]
	v_cmp_eq_u32_e64 s[14:15], 19, v81
	s_nop 1
	v_cndmask_b32_e64 v11, 0, 1.0, s[14:15]
	v_cndmask_b32_e64 v59, 0, 1.0, s[14:15]
	v_cmp_eq_u32_e64 s[14:15], 24, v81
	s_nop 1
	v_cndmask_b32_e64 v12, 0, 1.0, s[14:15]
	v_cndmask_b32_e64 v60, 0, 1.0, s[14:15]
	v_cmp_eq_u32_e64 s[14:15], 25, v81
	s_nop 1
	v_cndmask_b32_e64 v13, 0, 1.0, s[14:15]
	v_cndmask_b32_e64 v61, 0, 1.0, s[14:15]
	v_cmp_eq_u32_e64 s[14:15], 26, v81
	s_nop 1
	v_cndmask_b32_e64 v14, 0, 1.0, s[14:15]
	v_cndmask_b32_e64 v62, 0, 1.0, s[14:15]
	v_cmp_eq_u32_e64 s[14:15], 27, v81
	s_nop 1
	v_cndmask_b32_e64 v15, 0, 1.0, s[14:15]
	v_cndmask_b32_e64 v63, 0, 1.0, s[14:15]
	s_waitcnt vmcnt(15)
	v_lshlrev_b32_e32 v78, 16, v224
	v_mul_f32_e32 v78, 0xbfb8aa3b, v78
	v_exp_f32_e32 v78, v78
	v_lshlrev_b32_e32 v79, 16, v225
	v_lshlrev_b32_e32 v80, 16, v226
	ds_write2st64_b32 v77, v78, v79 offset0:0 offset1:1
	ds_write_b32 v77, v80 offset:512
	v_lshlrev_b32_e32 v240, 16, v227
	v_lshlrev_b32_e32 v241, 16, v228
	v_lshlrev_b32_e32 v244, 16, v244
	v_mov_b32_e32 v245, 0
	s_nop 0
	s_nop 0
	v_permlane32_swap_b32_e32 v244, v245
	ds_read_b128 v[148:151], v76 offset:0
	ds_read_b128 v[152:155], v76 offset:32
	ds_read_b128 v[156:159], v76 offset:64
	ds_read_b128 v[160:163], v76 offset:96
	ds_read_b128 v[164:167], v76 offset:128
	ds_read_b128 v[168:171], v76 offset:160
	ds_read_b128 v[172:175], v76 offset:192
	ds_read_b128 v[176:179], v76 offset:224
	s_movk_i32 s41, 0
	s_sleep 9
